# sp1 knorm item: 8 row-group loads issued together, one wait, batched bpermute reduction rounds (same arithmetic order) instead of 8 serialized load+3 LDS round trips
# speedup vs baseline: 1.0044x; 1.0036x over previous
; __device__ __forceinline__ float bflo(unsigned u) { return __uint_as_float(u << 16); }
; __device__ __forceinline__ float bfhi(unsigned u) { return __uint_as_float(u & 0xffff0000u); }
; __device__ __forceinline__ float sx(float v, int m, int lane) { return __builtin_bit_cast(float, __builtin_amdgcn_ds_bpermute((lane ^ m) << 2, __builtin_bit_cast(int, v))); }
; __device__ __forceinline__ void knorm_item(const bf16_t* hbuf, float* kmax2, int item, int lane) {
;     const int bh = item / NCHUNK, n = item % NCHUNK, b = bh / 6, h = bh % 6; const size_t t0 = (size_t)b * SEQ + (size_t)n * 64;
;     const int cr = lane >> 3, dc = lane & 7; float mx = 0.f;
; #pragma unroll
;     for (int i = 0; i < 8; ++i) { const u32x4 v = *(const u32x4*)(hbuf + (t0 + cr + 8 * i) * INWP + C_SBK + h * 64 + 8 * dc);
;         float s = bflo(v.x) * bflo(v.x) + bfhi(v.x) * bfhi(v.x) + bflo(v.y) * bflo(v.y) + bfhi(v.y) * bfhi(v.y) + bflo(v.z) * bflo(v.z) + bfhi(v.z) * bfhi(v.z) + bflo(v.w) * bflo(v.w) + bfhi(v.w) * bfhi(v.w);
;         s += sx(s, 1, lane); s += sx(s, 2, lane); s += sx(s, 4, lane); mx = fmaxf(mx, s); }
.LBB0_344:
	s_ashr_i32 s0, s12, 31
	s_lshr_b32 s0, s0, 24
	s_add_i32 s0, s12, s0
	s_mul_hi_i32 s1, s12, 0x2aaaaaab
	s_ashr_i32 s20, s0, 8
	s_lshr_b32 s15, s1, 31
	s_ashr_i32 s1, s1, 8
	s_add_i32 s22, s1, s15
	s_mul_hi_i32 s1, s20, 0x2aaaaaab
	s_lshr_b32 s15, s1, 31
	s_and_b32 s0, s0, 0xffffff00
	s_add_i32 s1, s1, s15
	s_sub_i32 s0, s12, s0
	s_mul_i32 s1, s1, 6
	s_sub_i32 s15, s20, s1
	s_ashr_i32 s23, s22, 31
	s_ashr_i32 s1, s0, 31
	s_lshl_b64 s[22:23], s[22:23], 14
	s_lshl_b64 s[0:1], s[0:1], 6
	s_add_u32 s0, s22, s0
	v_or_b32_e32 v2, s0, v24
	s_waitcnt lgkmcnt(0)
	v_mov_b64_e32 v[0:1], s[42:43]
	s_addc_u32 s17, s23, s1
	s_lshl_b32 s0, s15, 6
	v_mad_u64_u32 v[0:1], s[22:23], v2, s5, v[0:1]
	s_ashr_i32 s1, s0, 31
	v_mad_i32_i24 v1, s17, v207, v1
	v_lshl_add_u64 v[0:1], s[0:1], 1, v[0:1]
	v_lshl_add_u64 v[0:1], v[0:1], 0, v[32:33]
	global_load_dwordx4 v[10:13], v[0:1], off offset:1280
	s_mov_b32 s99, 0
	s_mov_b32 s98, 0xc000
	v_lshl_add_u64 v[2:3], s[98:99], 0, v[0:1]
	global_load_dwordx4 v[92:95], v[2:3], off offset:1280
	s_mov_b32 s98, 0x18000
	v_lshl_add_u64 v[2:3], s[98:99], 0, v[0:1]
	global_load_dwordx4 v[96:99], v[2:3], off offset:1280
	s_mov_b32 s98, 0x24000
	v_lshl_add_u64 v[2:3], s[98:99], 0, v[0:1]
	global_load_dwordx4 v[100:103], v[2:3], off offset:1280
	s_mov_b32 s98, 0x30000
	v_lshl_add_u64 v[2:3], s[98:99], 0, v[0:1]
	global_load_dwordx4 v[104:107], v[2:3], off offset:1280
	s_mov_b32 s98, 0x3c000
	v_lshl_add_u64 v[2:3], s[98:99], 0, v[0:1]
	global_load_dwordx4 v[108:111], v[2:3], off offset:1280
	s_mov_b32 s98, 0x48000
	v_lshl_add_u64 v[2:3], s[98:99], 0, v[0:1]
	global_load_dwordx4 v[112:115], v[2:3], off offset:1280
	s_mov_b32 s98, 0x54000
	v_lshl_add_u64 v[2:3], s[98:99], 0, v[0:1]
	global_load_dwordx4 v[116:119], v[2:3], off offset:1280
	s_waitcnt vmcnt(0)
	v_and_b32_e32 v120, 0xffff0000, v10
	v_lshlrev_b32_e32 v2, 16, v10
	v_mul_f32_e32 v120, v120, v120
	v_fmac_f32_e32 v120, v2, v2
	v_lshlrev_b32_e32 v2, 16, v11
	v_fmac_f32_e32 v120, v2, v2
	v_and_b32_e32 v2, 0xffff0000, v11
	v_fmac_f32_e32 v120, v2, v2
	v_lshlrev_b32_e32 v2, 16, v12
	v_fmac_f32_e32 v120, v2, v2
	v_and_b32_e32 v2, 0xffff0000, v12
	v_fmac_f32_e32 v120, v2, v2
	v_lshlrev_b32_e32 v2, 16, v13
	v_fmac_f32_e32 v120, v2, v2
	v_and_b32_e32 v2, 0xffff0000, v13
	v_fmac_f32_e32 v120, v2, v2
	v_and_b32_e32 v121, 0xffff0000, v92
	v_lshlrev_b32_e32 v2, 16, v92
	v_mul_f32_e32 v121, v121, v121
	v_fmac_f32_e32 v121, v2, v2
	v_lshlrev_b32_e32 v2, 16, v93
	v_fmac_f32_e32 v121, v2, v2
	v_and_b32_e32 v2, 0xffff0000, v93
	v_fmac_f32_e32 v121, v2, v2
	v_lshlrev_b32_e32 v2, 16, v94
	v_fmac_f32_e32 v121, v2, v2
	v_and_b32_e32 v2, 0xffff0000, v94
	v_fmac_f32_e32 v121, v2, v2
	v_lshlrev_b32_e32 v2, 16, v95
	v_fmac_f32_e32 v121, v2, v2
	v_and_b32_e32 v2, 0xffff0000, v95
	v_fmac_f32_e32 v121, v2, v2
	v_and_b32_e32 v122, 0xffff0000, v96
	v_lshlrev_b32_e32 v2, 16, v96
	v_mul_f32_e32 v122, v122, v122
	v_fmac_f32_e32 v122, v2, v2
	v_lshlrev_b32_e32 v2, 16, v97
	v_fmac_f32_e32 v122, v2, v2
	v_and_b32_e32 v2, 0xffff0000, v97
	v_fmac_f32_e32 v122, v2, v2
	v_lshlrev_b32_e32 v2, 16, v98
	v_fmac_f32_e32 v122, v2, v2
	v_and_b32_e32 v2, 0xffff0000, v98
	v_fmac_f32_e32 v122, v2, v2
	v_lshlrev_b32_e32 v2, 16, v99
	v_fmac_f32_e32 v122, v2, v2
	v_and_b32_e32 v2, 0xffff0000, v99
	v_fmac_f32_e32 v122, v2, v2
	v_and_b32_e32 v123, 0xffff0000, v100
	v_lshlrev_b32_e32 v2, 16, v100
	v_mul_f32_e32 v123, v123, v123
	v_fmac_f32_e32 v123, v2, v2
	v_lshlrev_b32_e32 v2, 16, v101
	v_fmac_f32_e32 v123, v2, v2
	v_and_b32_e32 v2, 0xffff0000, v101
	v_fmac_f32_e32 v123, v2, v2
	v_lshlrev_b32_e32 v2, 16, v102
	v_fmac_f32_e32 v123, v2, v2
	v_and_b32_e32 v2, 0xffff0000, v102
	v_fmac_f32_e32 v123, v2, v2
	v_lshlrev_b32_e32 v2, 16, v103
	v_fmac_f32_e32 v123, v2, v2
	v_and_b32_e32 v2, 0xffff0000, v103
	v_fmac_f32_e32 v123, v2, v2
	v_and_b32_e32 v124, 0xffff0000, v104
	v_lshlrev_b32_e32 v2, 16, v104
	v_mul_f32_e32 v124, v124, v124
	v_fmac_f32_e32 v124, v2, v2
	v_lshlrev_b32_e32 v2, 16, v105
	v_fmac_f32_e32 v124, v2, v2
	v_and_b32_e32 v2, 0xffff0000, v105
	v_fmac_f32_e32 v124, v2, v2
	v_lshlrev_b32_e32 v2, 16, v106
	v_fmac_f32_e32 v124, v2, v2
	v_and_b32_e32 v2, 0xffff0000, v106
	v_fmac_f32_e32 v124, v2, v2
	v_lshlrev_b32_e32 v2, 16, v107
	v_fmac_f32_e32 v124, v2, v2
	v_and_b32_e32 v2, 0xffff0000, v107
	v_fmac_f32_e32 v124, v2, v2
	v_and_b32_e32 v125, 0xffff0000, v108
	v_lshlrev_b32_e32 v2, 16, v108
	v_mul_f32_e32 v125, v125, v125
	v_fmac_f32_e32 v125, v2, v2
	v_lshlrev_b32_e32 v2, 16, v109
	v_fmac_f32_e32 v125, v2, v2
	v_and_b32_e32 v2, 0xffff0000, v109
	v_fmac_f32_e32 v125, v2, v2
	v_lshlrev_b32_e32 v2, 16, v110
	v_fmac_f32_e32 v125, v2, v2
	v_and_b32_e32 v2, 0xffff0000, v110
	v_fmac_f32_e32 v125, v2, v2
	v_lshlrev_b32_e32 v2, 16, v111
	v_fmac_f32_e32 v125, v2, v2
	v_and_b32_e32 v2, 0xffff0000, v111
	v_fmac_f32_e32 v125, v2, v2
	v_and_b32_e32 v126, 0xffff0000, v112
	v_lshlrev_b32_e32 v2, 16, v112
	v_mul_f32_e32 v126, v126, v126
	v_fmac_f32_e32 v126, v2, v2
	v_lshlrev_b32_e32 v2, 16, v113
	v_fmac_f32_e32 v126, v2, v2
	v_and_b32_e32 v2, 0xffff0000, v113
	v_fmac_f32_e32 v126, v2, v2
	v_lshlrev_b32_e32 v2, 16, v114
	v_fmac_f32_e32 v126, v2, v2
	v_and_b32_e32 v2, 0xffff0000, v114
	v_fmac_f32_e32 v126, v2, v2
	v_lshlrev_b32_e32 v2, 16, v115
	v_fmac_f32_e32 v126, v2, v2
	v_and_b32_e32 v2, 0xffff0000, v115
	v_fmac_f32_e32 v126, v2, v2
	v_and_b32_e32 v127, 0xffff0000, v116
	v_lshlrev_b32_e32 v2, 16, v116
	v_mul_f32_e32 v127, v127, v127
	v_fmac_f32_e32 v127, v2, v2
	v_lshlrev_b32_e32 v2, 16, v117
	v_fmac_f32_e32 v127, v2, v2
	v_and_b32_e32 v2, 0xffff0000, v117
	v_fmac_f32_e32 v127, v2, v2
	v_lshlrev_b32_e32 v2, 16, v118
	v_fmac_f32_e32 v127, v2, v2
	v_and_b32_e32 v2, 0xffff0000, v118
	v_fmac_f32_e32 v127, v2, v2
	v_lshlrev_b32_e32 v2, 16, v119
	v_fmac_f32_e32 v127, v2, v2
	v_and_b32_e32 v2, 0xffff0000, v119
	v_fmac_f32_e32 v127, v2, v2
	ds_bpermute_b32 v128, v4, v120
	ds_bpermute_b32 v129, v4, v121
	ds_bpermute_b32 v130, v4, v122
	ds_bpermute_b32 v131, v4, v123
	ds_bpermute_b32 v132, v4, v124
	ds_bpermute_b32 v133, v4, v125
	ds_bpermute_b32 v134, v4, v126
	ds_bpermute_b32 v135, v4, v127
	s_waitcnt lgkmcnt(0)
; __device__ __forceinline__ float bflo(unsigned u) { return __uint_as_float(u << 16); }
; __device__ __forceinline__ float bfhi(unsigned u) { return __uint_as_float(u & 0xffff0000u); }
; __device__ __forceinline__ float sx(float v, int m, int lane) { return __builtin_bit_cast(float, __builtin_amdgcn_ds_bpermute((lane ^ m) << 2, __builtin_bit_cast(int, v))); }
; __device__ __forceinline__ void knorm_item(const bf16_t* hbuf, float* kmax2, int item, int lane) {
;     ...
;     for (int i = 0; i < 8; ++i) { const u32x4 v = *(const u32x4*)(hbuf + (t0 + cr + 8 * i) * INWP + C_SBK + h * 64 + 8 * dc);
;         float s = bflo(v.x) * bflo(v.x) + bfhi(v.x) * bfhi(v.x) + bflo(v.y) * bflo(v.y) + bfhi(v.y) * bfhi(v.y) + bflo(v.z) * bflo(v.z) + bfhi(v.z) * bfhi(v.z) + bflo(v.w) * bflo(v.w) + bfhi(v.w) * bfhi(v.w);
;         s += sx(s, 1, lane); s += sx(s, 2, lane); s += sx(s, 4, lane); mx = fmaxf(mx, s); }
;     mx = fmaxf(mx, sx(mx, 8, lane)); mx = fmaxf(mx, sx(mx, 16, lane)); mx = fmaxf(mx, sx(mx, 32, lane));
;     if (lane == 0) atomicMax((unsigned*)kmax2 + bh, __float_as_uint(mx));
	v_add_f32_e32 v120, v120, v128
	v_add_f32_e32 v121, v121, v129
	v_add_f32_e32 v122, v122, v130
	v_add_f32_e32 v123, v123, v131
	v_add_f32_e32 v124, v124, v132
	v_add_f32_e32 v125, v125, v133
	v_add_f32_e32 v126, v126, v134
	v_add_f32_e32 v127, v127, v135
	ds_bpermute_b32 v128, v5, v120
	ds_bpermute_b32 v129, v5, v121
	ds_bpermute_b32 v130, v5, v122
	ds_bpermute_b32 v131, v5, v123
	ds_bpermute_b32 v132, v5, v124
	ds_bpermute_b32 v133, v5, v125
	ds_bpermute_b32 v134, v5, v126
	ds_bpermute_b32 v135, v5, v127
	s_waitcnt lgkmcnt(0)
	v_add_f32_e32 v120, v120, v128
	v_add_f32_e32 v121, v121, v129
	v_add_f32_e32 v122, v122, v130
	v_add_f32_e32 v123, v123, v131
	v_add_f32_e32 v124, v124, v132
	v_add_f32_e32 v125, v125, v133
	v_add_f32_e32 v126, v126, v134
	v_add_f32_e32 v127, v127, v135
	ds_bpermute_b32 v128, v6, v120
	ds_bpermute_b32 v129, v6, v121
	ds_bpermute_b32 v130, v6, v122
	ds_bpermute_b32 v131, v6, v123
	ds_bpermute_b32 v132, v6, v124
	ds_bpermute_b32 v133, v6, v125
	ds_bpermute_b32 v134, v6, v126
	ds_bpermute_b32 v135, v6, v127
	s_waitcnt lgkmcnt(0)
	v_add_f32_e32 v120, v120, v128
	v_add_f32_e32 v121, v121, v129
	v_add_f32_e32 v122, v122, v130
	v_add_f32_e32 v123, v123, v131
	v_add_f32_e32 v124, v124, v132
	v_add_f32_e32 v125, v125, v133
	v_add_f32_e32 v126, v126, v134
	v_add_f32_e32 v127, v127, v135
	v_mov_b32_e32 v14, v120
	v_max3_f32 v14, v14, 0, v121
	v_mov_b32_e32 v15, v122
	v_max3_f32 v14, v14, v15, v123
	v_mov_b32_e32 v15, v124
	v_max3_f32 v10, v14, v15, v125
	v_mov_b32_e32 v11, v126
	v_max3_f32 v0, v10, v11, v127
	ds_bpermute_b32 v1, v7, v0
	s_waitcnt lgkmcnt(0)
	v_max_f32_e32 v1, v1, v1
	v_max_f32_e32 v0, v0, v1
	ds_bpermute_b32 v1, v8, v0
	s_waitcnt lgkmcnt(0)
	v_max_f32_e32 v1, v1, v1
	v_max_f32_e32 v0, v0, v1
	ds_bpermute_b32 v1, v9, v0
	s_and_saveexec_b64 s[22:23], vcc
	s_cbranch_execz .LBB0_343
	s_waitcnt lgkmcnt(0)
	v_max_f32_e32 v1, v1, v1
	v_max_f32_e32 v0, v0, v0
	s_mov_b64 s[0:1], exec
	v_max_f32_e32 v0, v0, v1
	s_mov_b32 s15, 0
